# P0a pool-weight fold rewritten by hand: all 25 loads issued up front, 64-row chunks double-buffered in LDS, same fma order
# baseline (speedup 1.0000x reference)
; __device__ __forceinline__ void fold_item(unsigned char* lds, const float* __restrict__ w_in_pool, const float* __restrict__ w_pool_group, const float* __restrict__ pool_scale, const float* __restrict__ g_mix,
;                                           bf16_t* WT, int item, int tid) {
;     const int jl = item >> 7, grp = (item >> 5) & 3, k0 = (item & 31) * 32;
;     float* wt = (float*)lds;
;     float* wg = (float*)(lds + 32 * 196 * 4);
;     unsigned short* ot = (unsigned short*)(lds + 32 * 196 * 4 + 48 * 192 * 4);
;     const float* wsrc = w_in_pool + ((size_t)jl * D + k0) * D + grp * 192;
;     const float* gsrc = w_pool_group + (size_t)(jl * 4 + grp) * 192 * 192;
;     __syncthreads();
;     for (int i = tid; i < 32 * 48; i += 512) { const int r = i / 48, c4 = i - r * 48; *(f32x4*)(wt + r * 196 + c4 * 4) = *(const f32x4*)(wsrc + (size_t)r * D + c4 * 4); }
;     const int k = tid >> 4, cc = (tid & 15) * 12;
;     float acc[12];
; #pragma unroll
;     for (int e = 0; e < 12; ++e) acc[e] = 0.f;
;     for (int jc = 0; jc < 4; ++jc) {
;         __syncthreads();
;         for (int i = tid; i < 48 * 48; i += 512) *(f32x4*)(wg + i * 4) = *(const f32x4*)(gsrc + (size_t)jc * 48 * 192 + i * 4);
;         __syncthreads();
; __global__ void __launch_bounds__(512, 2) fwd_kernel(Params p) {
;     ...
;         for (int item = bid; item < 256; item += G) fold_item(lds, w_in_pool, w_pool_group, pool_scale, g_mix, WT, item, tid);
.Lft_done:
	s_waitcnt vmcnt(0) lgkmcnt(0)
	s_barrier
	v_lshrrev_b32_e32 v0, 4, v204
	v_and_b32_e32 v1, 15, v204
	v_lshlrev_b32_e32 v229, 4, v204
	v_lshlrev_b32_e32 v228, 12, v0
	v_lshl_add_u32 v228, v1, 4, v228
	v_mul_u32_u24_e32 v230, 48, v1
	v_lshlrev_b32_e32 v231, 2, v0
	s_movk_i32 s40, 0x310
	v_mul_u32_u24_e32 v235, s40, v0
	v_lshl_add_u32 v232, v1, 4, v235
	v_add_u32_e32 v233, 0x6200, v229
	v_add_u32_e32 v234, 0x12200, v229
	s_movk_i32 s40, 0x3c0
	v_mul_u32_u24_e32 v237, s40, v1
	v_lshl_add_u32 v237, v0, 1, v237
	v_add_u32_e32 v237, 0x1e200, v237
	v_readlane_b32 s34, v252, 0
	s_nop 3
.Lfold_loop:
	s_cmp_gt_u32 s34, 0xff
	s_cbranch_scc1 .Lfold_done
	s_lshr_b32 s35, s34, 7
	s_bfe_u32 s36, s34, 0x20005
	s_and_b32 s37, s34, 31
	s_lshl_b32 s40, s35, 22
	s_lshl_b32 s41, s37, 17
	s_add_u32 s40, s40, s41
	s_mul_i32 s41, s36, 0x300
	s_add_u32 s40, s40, s41
	s_add_u32 s42, s22, s40
	s_addc_u32 s43, s23, 0
	s_lshl_b32 s40, s35, 2
	s_add_u32 s40, s40, s36
	s_mul_i32 s40, s40, 0x24000
	s_add_u32 s44, s24, s40
	s_addc_u32 s45, s25, 0
	s_mul_i32 s40, s35, 0x700000
	s_mul_i32 s41, s36, 0x60000
	s_add_u32 s40, s40, s41
	s_lshl_b32 s41, s37, 6
	s_add_u32 s40, s40, s41
	s_add_u32 s46, s64, s40
	s_addc_u32 s47, s65, 0
	s_lshl_b32 s40, s35, 13
	s_lshl_b32 s41, s37, 7
	s_add_u32 s40, s40, s41
	s_add_u32 s48, s16, s40
	s_addc_u32 s49, s17, 0
	s_mul_i32 s40, s35, 0xc00
	s_mul_i32 s41, s36, 0x300
	s_add_u32 s40, s40, s41
	s_add_u32 s50, s26, s40
	s_addc_u32 s51, s27, 0
	global_load_dwordx4 v[76:79], v228, s[42:43]
	global_load_dwordx4 v[80:83], v228, s[42:43] offset:256
	global_load_dwordx4 v[84:87], v228, s[42:43] offset:512
	global_load_dwordx4 v[88:91], v229, s[44:45]
	s_add_u32 s44, s44, 0x2000
	s_addc_u32 s45, s45, 0
	global_load_dwordx4 v[92:95], v229, s[44:45]
	s_add_u32 s44, s44, 0x2000
	s_addc_u32 s45, s45, 0
	global_load_dwordx4 v[96:99], v229, s[44:45]
	s_add_u32 s44, s44, 0x2000
	s_addc_u32 s45, s45, 0
	global_load_dwordx4 v[100:103], v229, s[44:45]
	s_add_u32 s44, s44, 0x2000
	s_addc_u32 s45, s45, 0
	global_load_dwordx4 v[104:107], v229, s[44:45]
	s_add_u32 s44, s44, 0x2000
	s_addc_u32 s45, s45, 0
	global_load_dwordx4 v[108:111], v229, s[44:45]
	s_add_u32 s44, s44, 0x2000
	s_addc_u32 s45, s45, 0
	global_load_dwordx4 v[112:115], v229, s[44:45]
	s_add_u32 s44, s44, 0x2000
	s_addc_u32 s45, s45, 0
	global_load_dwordx4 v[116:119], v229, s[44:45]
	s_add_u32 s44, s44, 0x2000
	s_addc_u32 s45, s45, 0
	global_load_dwordx4 v[120:123], v229, s[44:45]
	s_add_u32 s44, s44, 0x2000
	s_addc_u32 s45, s45, 0
	global_load_dwordx4 v[124:127], v229, s[44:45]
	s_add_u32 s44, s44, 0x2000
	s_addc_u32 s45, s45, 0
	global_load_dwordx4 v[128:131], v229, s[44:45]
	s_add_u32 s44, s44, 0x2000
	s_addc_u32 s45, s45, 0
	global_load_dwordx4 v[132:135], v229, s[44:45]
	s_add_u32 s44, s44, 0x2000
	s_addc_u32 s45, s45, 0
	global_load_dwordx4 v[172:175], v229, s[44:45]
	s_add_u32 s44, s44, 0x2000
	s_addc_u32 s45, s45, 0
	global_load_dwordx4 v[176:179], v229, s[44:45]
	s_add_u32 s44, s44, 0x2000
	s_addc_u32 s45, s45, 0
	global_load_dwordx4 v[180:183], v229, s[44:45]
	s_add_u32 s44, s44, 0x2000
	s_addc_u32 s45, s45, 0
	global_load_dwordx4 v[184:187], v229, s[44:45]
	s_add_u32 s44, s44, 0x2000
	s_addc_u32 s45, s45, 0
	global_load_dwordx4 v[188:191], v229, s[44:45]
	s_add_u32 s44, s44, 0x2000
	s_addc_u32 s45, s45, 0
	global_load_dwordx4 v[192:195], v229, s[44:45]
	s_add_u32 s44, s44, 0x2000
	s_addc_u32 s45, s45, 0
	global_load_dwordx4 v[196:199], v230, s[50:51]
	global_load_dwordx4 v[200:203], v230, s[50:51] offset:16
	global_load_dwordx4 v[208:211], v230, s[50:51] offset:32
	global_load_dword v2, v231, s[48:49]
	v_mov_b32_e32 v64, 0
	v_mov_b32_e32 v65, 0
	v_mov_b32_e32 v66, 0
	v_mov_b32_e32 v67, 0
	v_mov_b32_e32 v68, 0
	v_mov_b32_e32 v69, 0
	v_mov_b32_e32 v70, 0
	v_mov_b32_e32 v71, 0
	v_mov_b32_e32 v72, 0
	v_mov_b32_e32 v73, 0
	v_mov_b32_e32 v74, 0
	v_mov_b32_e32 v75, 0
	s_waitcnt vmcnt(16)
	ds_write_b128 v232, v[76:79]
	ds_write_b128 v232, v[80:83] offset:256
	ds_write_b128 v232, v[84:87] offset:512
	ds_write_b128 v233, v[88:91]
	ds_write_b128 v233, v[92:95] offset:8192
	ds_write_b128 v233, v[96:99] offset:16384
	ds_write_b128 v233, v[100:103] offset:24576
	ds_write_b128 v233, v[104:107] offset:32768
	ds_write_b128 v233, v[108:111] offset:40960
	s_waitcnt vmcnt(10)
	ds_write_b128 v234, v[112:115]
	ds_write_b128 v234, v[116:119] offset:8192
	ds_write_b128 v234, v[120:123] offset:16384
	ds_write_b128 v234, v[124:127] offset:24576
	ds_write_b128 v234, v[128:131] offset:32768
	ds_write_b128 v234, v[132:135] offset:40960
	s_waitcnt lgkmcnt(0)
	s_barrier
	v_mul_u32_u24_e32 v236, 48, v1
	v_add_u32_e32 v236, 0x6200, v236
	v_add_u32_e32 v216, 0x0, v235
	s_mov_b32 s55, 0
; __device__ __forceinline__ void fold_item(unsigned char* lds, const float* __restrict__ w_in_pool, const float* __restrict__ w_pool_group, const float* __restrict__ pool_scale, const float* __restrict__ g_mix,
;                                           bf16_t* WT, int item, int tid) {
;     ...
; #pragma unroll 4
;         for (int jj = 0; jj < 48; ++jj) {
;             const float a = wt[k * 196 + jc * 48 + jj];
;             const f32x4 b0 = *(const f32x4*)(wg + jj * 192 + cc), b1 = *(const f32x4*)(wg + jj * 192 + cc + 4), b2 = *(const f32x4*)(wg + jj * 192 + cc + 8);
;             acc[0] += a * b0.x; acc[1] += a * b0.y; acc[2] += a * b0.z; acc[3] += a * b0.w;
;             acc[4] += a * b1.x; acc[5] += a * b1.y; acc[6] += a * b1.z; acc[7] += a * b1.w;
;             acc[8] += a * b2.x; acc[9] += a * b2.y; acc[10] += a * b2.z; acc[11] += a * b2.w;
;         }
.Lfold_c0:
	ds_read_b128 v[212:215], v216
	ds_read_b128 v[88:91], v236
	ds_read_b128 v[92:95], v236 offset:16
	ds_read_b128 v[96:99], v236 offset:32
	ds_read_b128 v[100:103], v236 offset:768
	ds_read_b128 v[104:107], v236 offset:784
	ds_read_b128 v[108:111], v236 offset:800
	ds_read_b128 v[112:115], v236 offset:1536
	ds_read_b128 v[116:119], v236 offset:1552
	ds_read_b128 v[120:123], v236 offset:1568
	ds_read_b128 v[124:127], v236 offset:2304
	ds_read_b128 v[128:131], v236 offset:2320
	ds_read_b128 v[132:135], v236 offset:2336
	v_add_u32_e32 v216, 16, v216
	v_add_u32_e32 v236, 0xc00, v236
	s_waitcnt lgkmcnt(11)
	v_fmac_f32_e32 v64, v212, v88
	v_fmac_f32_e32 v65, v212, v89
	v_fmac_f32_e32 v66, v212, v90
	v_fmac_f32_e32 v67, v212, v91
	s_waitcnt lgkmcnt(10)
	v_fmac_f32_e32 v68, v212, v92
	v_fmac_f32_e32 v69, v212, v93
	v_fmac_f32_e32 v70, v212, v94
	v_fmac_f32_e32 v71, v212, v95
	s_waitcnt lgkmcnt(9)
	v_fmac_f32_e32 v72, v212, v96
	v_fmac_f32_e32 v73, v212, v97
	v_fmac_f32_e32 v74, v212, v98
	v_fmac_f32_e32 v75, v212, v99
	s_waitcnt lgkmcnt(8)
	v_fmac_f32_e32 v64, v213, v100
	v_fmac_f32_e32 v65, v213, v101
	v_fmac_f32_e32 v66, v213, v102
	v_fmac_f32_e32 v67, v213, v103
	s_waitcnt lgkmcnt(7)
	v_fmac_f32_e32 v68, v213, v104
	v_fmac_f32_e32 v69, v213, v105
	v_fmac_f32_e32 v70, v213, v106
	v_fmac_f32_e32 v71, v213, v107
	s_waitcnt lgkmcnt(6)
	v_fmac_f32_e32 v72, v213, v108
	v_fmac_f32_e32 v73, v213, v109
	v_fmac_f32_e32 v74, v213, v110
	v_fmac_f32_e32 v75, v213, v111
	s_waitcnt lgkmcnt(5)
	v_fmac_f32_e32 v64, v214, v112
	v_fmac_f32_e32 v65, v214, v113
	v_fmac_f32_e32 v66, v214, v114
	v_fmac_f32_e32 v67, v214, v115
	s_waitcnt lgkmcnt(4)
	v_fmac_f32_e32 v68, v214, v116
	v_fmac_f32_e32 v69, v214, v117
	v_fmac_f32_e32 v70, v214, v118
	v_fmac_f32_e32 v71, v214, v119
	s_waitcnt lgkmcnt(3)
	v_fmac_f32_e32 v72, v214, v120
	v_fmac_f32_e32 v73, v214, v121
	v_fmac_f32_e32 v74, v214, v122
	v_fmac_f32_e32 v75, v214, v123
	s_waitcnt lgkmcnt(2)
	v_fmac_f32_e32 v64, v215, v124
	v_fmac_f32_e32 v65, v215, v125
	v_fmac_f32_e32 v66, v215, v126
	v_fmac_f32_e32 v67, v215, v127
	s_waitcnt lgkmcnt(1)
	v_fmac_f32_e32 v68, v215, v128
	v_fmac_f32_e32 v69, v215, v129
	v_fmac_f32_e32 v70, v215, v130
	v_fmac_f32_e32 v71, v215, v131
	s_waitcnt lgkmcnt(0)
	v_fmac_f32_e32 v72, v215, v132
	v_fmac_f32_e32 v73, v215, v133
	v_fmac_f32_e32 v74, v215, v134
	v_fmac_f32_e32 v75, v215, v135
	s_add_i32 s55, s55, 1
	s_cmp_lt_u32 s55, 16
	s_cbranch_scc1 .Lfold_c0
	v_mul_u32_u24_e32 v236, 48, v1
	v_add_u32_e32 v236, 0x12200, v236
	v_add_u32_e32 v216, 0x100, v235
	s_mov_b32 s55, 0
.Lfold_c1:
	ds_read_b128 v[212:215], v216
	ds_read_b128 v[88:91], v236
	ds_read_b128 v[92:95], v236 offset:16
	ds_read_b128 v[96:99], v236 offset:32
	ds_read_b128 v[100:103], v236 offset:768
	ds_read_b128 v[104:107], v236 offset:784
	ds_read_b128 v[108:111], v236 offset:800
	ds_read_b128 v[112:115], v236 offset:1536
	ds_read_b128 v[116:119], v236 offset:1552
	ds_read_b128 v[120:123], v236 offset:1568
	ds_read_b128 v[124:127], v236 offset:2304
	ds_read_b128 v[128:131], v236 offset:2320
	ds_read_b128 v[132:135], v236 offset:2336
	v_add_u32_e32 v216, 16, v216
	v_add_u32_e32 v236, 0xc00, v236
	s_waitcnt lgkmcnt(11)
	v_fmac_f32_e32 v64, v212, v88
	v_fmac_f32_e32 v65, v212, v89
	v_fmac_f32_e32 v66, v212, v90
	v_fmac_f32_e32 v67, v212, v91
	s_waitcnt lgkmcnt(10)
	v_fmac_f32_e32 v68, v212, v92
	v_fmac_f32_e32 v69, v212, v93
	v_fmac_f32_e32 v70, v212, v94
	v_fmac_f32_e32 v71, v212, v95
	s_waitcnt lgkmcnt(9)
	v_fmac_f32_e32 v72, v212, v96
	v_fmac_f32_e32 v73, v212, v97
	v_fmac_f32_e32 v74, v212, v98
	v_fmac_f32_e32 v75, v212, v99
	s_waitcnt lgkmcnt(8)
	v_fmac_f32_e32 v64, v213, v100
	v_fmac_f32_e32 v65, v213, v101
	v_fmac_f32_e32 v66, v213, v102
	v_fmac_f32_e32 v67, v213, v103
	s_waitcnt lgkmcnt(7)
	v_fmac_f32_e32 v68, v213, v104
	v_fmac_f32_e32 v69, v213, v105
	v_fmac_f32_e32 v70, v213, v106
	v_fmac_f32_e32 v71, v213, v107
	s_waitcnt lgkmcnt(6)
	v_fmac_f32_e32 v72, v213, v108
	v_fmac_f32_e32 v73, v213, v109
	v_fmac_f32_e32 v74, v213, v110
	v_fmac_f32_e32 v75, v213, v111
	s_waitcnt lgkmcnt(5)
	v_fmac_f32_e32 v64, v214, v112
	v_fmac_f32_e32 v65, v214, v113
	v_fmac_f32_e32 v66, v214, v114
	v_fmac_f32_e32 v67, v214, v115
	s_waitcnt lgkmcnt(4)
	v_fmac_f32_e32 v68, v214, v116
	v_fmac_f32_e32 v69, v214, v117
	v_fmac_f32_e32 v70, v214, v118
	v_fmac_f32_e32 v71, v214, v119
	s_waitcnt lgkmcnt(3)
	v_fmac_f32_e32 v72, v214, v120
	v_fmac_f32_e32 v73, v214, v121
	v_fmac_f32_e32 v74, v214, v122
	v_fmac_f32_e32 v75, v214, v123
	s_waitcnt lgkmcnt(2)
	v_fmac_f32_e32 v64, v215, v124
	v_fmac_f32_e32 v65, v215, v125
	v_fmac_f32_e32 v66, v215, v126
	v_fmac_f32_e32 v67, v215, v127
	s_waitcnt lgkmcnt(1)
	v_fmac_f32_e32 v68, v215, v128
	v_fmac_f32_e32 v69, v215, v129
	v_fmac_f32_e32 v70, v215, v130
	v_fmac_f32_e32 v71, v215, v131
	s_waitcnt lgkmcnt(0)
	v_fmac_f32_e32 v72, v215, v132
	v_fmac_f32_e32 v73, v215, v133
	v_fmac_f32_e32 v74, v215, v134
	v_fmac_f32_e32 v75, v215, v135
	s_add_i32 s55, s55, 1
	s_cmp_lt_u32 s55, 16
	s_cbranch_scc1 .Lfold_c1
	s_barrier
	s_waitcnt vmcnt(4)
	ds_write_b128 v233, v[172:175]
	ds_write_b128 v233, v[176:179] offset:8192
	ds_write_b128 v233, v[180:183] offset:16384
	ds_write_b128 v233, v[184:187] offset:24576
	ds_write_b128 v233, v[188:191] offset:32768
	ds_write_b128 v233, v[192:195] offset:40960
	s_waitcnt lgkmcnt(0)
	s_barrier
	v_mul_u32_u24_e32 v236, 48, v1
	v_add_u32_e32 v236, 0x6200, v236
	v_add_u32_e32 v216, 0x200, v235
	s_mov_b32 s55, 0
; __device__ __forceinline__ unsigned cvt_pk_bf16(float lo, float hi) { unsigned r; asm volatile("v_cvt_pk_bf16_f32 %0, %1, %2" : "=v"(r) : "v"(lo), "v"(hi)); return r; }
; __device__ __forceinline__ void fold_item(unsigned char* lds, const float* __restrict__ w_in_pool, const float* __restrict__ w_pool_group, const float* __restrict__ pool_scale, const float* __restrict__ g_mix,
;                                           bf16_t* WT, int item, int tid) {
;     ...
;         }
;     }
;     const float gk = g_mix[(2 * jl) * D + k0 + k];
; #pragma unroll
;     for (int e = 0; e < 12; e += 2) { const float s0 = pool_scale[jl * 768 + grp * 192 + cc + e] * gk, s1 = pool_scale[jl * 768 + grp * 192 + cc + e + 1] * gk;
;         const unsigned w = cvt_pk_bf16(acc[e] * s0, acc[e + 1] * s1); ot[(cc + e) * 40 + k] = (unsigned short)(w & 0xffffu); ot[(cc + e + 1) * 40 + k] = (unsigned short)(w >> 16); }
;     __syncthreads();
;     bf16_t* dst = WT + wt_in(2 * jl) + (size_t)(grp * 192) * D + k0;
;     for (int i = tid; i < 192 * 4; i += 512) { const int c = i >> 2, part = i & 3; *(u32x4*)(dst + (size_t)c * D + part * 8) = *(const u32x4*)((const unsigned char*)ot + c * 80 + part * 16); }
.Lfold_c2:
	ds_read_b128 v[212:215], v216
	ds_read_b128 v[88:91], v236
	ds_read_b128 v[92:95], v236 offset:16
	ds_read_b128 v[96:99], v236 offset:32
	ds_read_b128 v[100:103], v236 offset:768
	ds_read_b128 v[104:107], v236 offset:784
	ds_read_b128 v[108:111], v236 offset:800
	ds_read_b128 v[112:115], v236 offset:1536
	ds_read_b128 v[116:119], v236 offset:1552
	ds_read_b128 v[120:123], v236 offset:1568
	ds_read_b128 v[124:127], v236 offset:2304
	ds_read_b128 v[128:131], v236 offset:2320
	ds_read_b128 v[132:135], v236 offset:2336
	v_add_u32_e32 v216, 16, v216
	v_add_u32_e32 v236, 0xc00, v236
	s_waitcnt lgkmcnt(11)
	v_fmac_f32_e32 v64, v212, v88
	v_fmac_f32_e32 v65, v212, v89
	v_fmac_f32_e32 v66, v212, v90
	v_fmac_f32_e32 v67, v212, v91
	s_waitcnt lgkmcnt(10)
	v_fmac_f32_e32 v68, v212, v92
	v_fmac_f32_e32 v69, v212, v93
	v_fmac_f32_e32 v70, v212, v94
	v_fmac_f32_e32 v71, v212, v95
	s_waitcnt lgkmcnt(9)
	v_fmac_f32_e32 v72, v212, v96
	v_fmac_f32_e32 v73, v212, v97
	v_fmac_f32_e32 v74, v212, v98
	v_fmac_f32_e32 v75, v212, v99
	s_waitcnt lgkmcnt(8)
	v_fmac_f32_e32 v64, v213, v100
	v_fmac_f32_e32 v65, v213, v101
	v_fmac_f32_e32 v66, v213, v102
	v_fmac_f32_e32 v67, v213, v103
	s_waitcnt lgkmcnt(7)
	v_fmac_f32_e32 v68, v213, v104
	v_fmac_f32_e32 v69, v213, v105
	v_fmac_f32_e32 v70, v213, v106
	v_fmac_f32_e32 v71, v213, v107
	s_waitcnt lgkmcnt(6)
	v_fmac_f32_e32 v72, v213, v108
	v_fmac_f32_e32 v73, v213, v109
	v_fmac_f32_e32 v74, v213, v110
	v_fmac_f32_e32 v75, v213, v111
	s_waitcnt lgkmcnt(5)
	v_fmac_f32_e32 v64, v214, v112
	v_fmac_f32_e32 v65, v214, v113
	v_fmac_f32_e32 v66, v214, v114
	v_fmac_f32_e32 v67, v214, v115
	s_waitcnt lgkmcnt(4)
	v_fmac_f32_e32 v68, v214, v116
	v_fmac_f32_e32 v69, v214, v117
	v_fmac_f32_e32 v70, v214, v118
	v_fmac_f32_e32 v71, v214, v119
	s_waitcnt lgkmcnt(3)
	v_fmac_f32_e32 v72, v214, v120
	v_fmac_f32_e32 v73, v214, v121
	v_fmac_f32_e32 v74, v214, v122
	v_fmac_f32_e32 v75, v214, v123
	s_waitcnt lgkmcnt(2)
	v_fmac_f32_e32 v64, v215, v124
	v_fmac_f32_e32 v65, v215, v125
	v_fmac_f32_e32 v66, v215, v126
	v_fmac_f32_e32 v67, v215, v127
	s_waitcnt lgkmcnt(1)
	v_fmac_f32_e32 v68, v215, v128
	v_fmac_f32_e32 v69, v215, v129
	v_fmac_f32_e32 v70, v215, v130
	v_fmac_f32_e32 v71, v215, v131
	s_waitcnt lgkmcnt(0)
	v_fmac_f32_e32 v72, v215, v132
	v_fmac_f32_e32 v73, v215, v133
	v_fmac_f32_e32 v74, v215, v134
	v_fmac_f32_e32 v75, v215, v135
	s_add_i32 s55, s55, 1
	s_cmp_lt_u32 s55, 16
	s_cbranch_scc1 .Lfold_c2
	s_waitcnt vmcnt(0)
	v_mul_f32_e32 v216, v196, v2
	v_mul_f32_e32 v217, v197, v2
	v_mul_f32_e32 v216, v64, v216
	v_mul_f32_e32 v217, v65, v217
	v_cvt_pk_bf16_f32 v218, v216, v217
	ds_write_b16 v237, v218
	ds_write_b16_d16_hi v237, v218 offset:80
	v_mul_f32_e32 v216, v198, v2
	v_mul_f32_e32 v217, v199, v2
	v_mul_f32_e32 v216, v66, v216
	v_mul_f32_e32 v217, v67, v217
	v_cvt_pk_bf16_f32 v218, v216, v217
	ds_write_b16 v237, v218 offset:160
	ds_write_b16_d16_hi v237, v218 offset:240
	v_mul_f32_e32 v216, v200, v2
	v_mul_f32_e32 v217, v201, v2
	v_mul_f32_e32 v216, v68, v216
	v_mul_f32_e32 v217, v69, v217
	v_cvt_pk_bf16_f32 v218, v216, v217
	ds_write_b16 v237, v218 offset:320
	ds_write_b16_d16_hi v237, v218 offset:400
	v_mul_f32_e32 v216, v202, v2
	v_mul_f32_e32 v217, v203, v2
	v_mul_f32_e32 v216, v70, v216
	v_mul_f32_e32 v217, v71, v217
	v_cvt_pk_bf16_f32 v218, v216, v217
	ds_write_b16 v237, v218 offset:480
	ds_write_b16_d16_hi v237, v218 offset:560
	v_mul_f32_e32 v216, v208, v2
	v_mul_f32_e32 v217, v209, v2
	v_mul_f32_e32 v216, v72, v216
	v_mul_f32_e32 v217, v73, v217
	v_cvt_pk_bf16_f32 v218, v216, v217
	ds_write_b16 v237, v218 offset:640
	ds_write_b16_d16_hi v237, v218 offset:720
	v_mul_f32_e32 v216, v210, v2
	v_mul_f32_e32 v217, v211, v2
	v_mul_f32_e32 v216, v74, v216
	v_mul_f32_e32 v217, v75, v217
	v_cvt_pk_bf16_f32 v218, v216, v217
	ds_write_b16 v237, v218 offset:800
	ds_write_b16_d16_hi v237, v218 offset:880
	s_waitcnt lgkmcnt(0)
	s_barrier
	v_lshrrev_b32_e32 v216, 2, v204
	v_and_b32_e32 v217, 3, v204
	v_mul_u32_u24_e32 v218, 80, v216
	v_lshl_add_u32 v218, v217, 4, v218
	v_add_u32_e32 v218, 0x1e200, v218
	v_lshlrev_b32_e32 v219, 11, v216
	v_lshl_add_u32 v219, v217, 4, v219
	ds_read_b128 v[220:223], v218
	s_waitcnt lgkmcnt(0)
	global_store_dwordx4 v219, v[220:223], s[46:47]
	v_cmp_gt_u32_e32 vcc, 0x100, v204
	s_and_saveexec_b64 s[56:57], vcc
	s_cbranch_execz .Lfold_cp2
	ds_read_b128 v[220:223], v218 offset:10240
	v_add_u32_e32 v219, 0x40000, v219
	s_waitcnt lgkmcnt(0)
	global_store_dwordx4 v219, v[220:223], s[46:47]
.Lfold_cp2:
	s_or_b64 exec, exec, s[56:57]
	s_add_u32 s34, s34, s68
	s_barrier
	s_branch .Lfold_loop

; __device__ __forceinline__ void fold_item(unsigned char* lds, const float* __restrict__ w_in_pool, const float* __restrict__ w_pool_group, const float* __restrict__ pool_scale, const float* __restrict__ g_mix,
;                                           bf16_t* WT, int item, int tid) {
;     const int jl = item >> 7, grp = (item >> 5) & 3, k0 = (item & 31) * 32;
;     float* wt = (float*)lds;
;     float* wg = (float*)(lds + 32 * 196 * 4);
;     unsigned short* ot = (unsigned short*)(lds + 32 * 196 * 4 + 48 * 192 * 4);
;     const float* wsrc = w_in_pool + ((size_t)jl * D + k0) * D + grp * 192;
;     const float* gsrc = w_pool_group + (size_t)(jl * 4 + grp) * 192 * 192;
;     __syncthreads();
;     for (int i = tid; i < 32 * 48; i += 512) { const int r = i / 48, c4 = i - r * 48; *(f32x4*)(wt + r * 196 + c4 * 4) = *(const f32x4*)(wsrc + (size_t)r * D + c4 * 4); }
;     const int k = tid >> 4, cc = (tid & 15) * 12;
; __global__ void __launch_bounds__(512, 2) fwd_kernel(Params p) {
;     ...
;         for (int item = bid; item < 256; item += G) fold_item(lds, w_in_pool, w_pool_group, pool_scale, g_mix, WT, item, tid);
.LBB0_230:
	s_or_b64 exec, exec, s[2:3]
	v_readlane_b32 s0, v252, 0
	s_cmpk_gt_i32 s0, 0xff
	s_movk_i32 s11, 0xff
	s_waitcnt lgkmcnt(0)
	s_barrier
	s_branch .LBB0_254
	v_and_b32_e32 v0, 15, v204
	s_waitcnt vmcnt(14)
	v_lshrrev_b32_e32 v26, 4, v204
	s_movk_i32 s0, 0x310
	v_mul_u32_u24_e32 v2, 0x1e0, v0
	s_waitcnt vmcnt(12)
	v_mul_u32_u24_e32 v27, 12, v0
	s_waitcnt vmcnt(10)
	v_mad_u32_u24 v28, v26, s0, 0
	v_mul_i32_i24_e32 v1, 0xfffffcf2, v26
	v_lshlrev_b32_e32 v2, 1, v2
	v_lshl_add_u32 v4, v27, 2, 0
	s_waitcnt vmcnt(8)
	v_add3_u32 v29, v28, v1, v2
	v_mul_u32_u24_e32 v0, 0x390, v0
	v_lshlrev_b32_e32 v1, 1, v26
	v_add3_u32 v30, v4, v0, v1
	v_and_b32_e32 v0, 3, v204
	v_lshlrev_b32_e32 v12, 4, v0
	v_lshlrev_b32_e32 v0, 4, v204
	v_add_u32_e32 v1, 0, v0
	s_movk_i32 s0, 0x300
	v_add_u32_e32 v32, 0x6200, v1
	v_mov_b32_e32 v1, 0
	v_lshrrev_b32_e32 v13, 2, v204
	v_cmp_gt_u32_e32 vcc, s0, v204
	v_lshl_add_u64 v[2:3], s[24:25], 0, v[0:1]
	s_mov_b64 s[0:1], 0x9000
	v_lshl_or_b32 v0, v13, 11, v12
	v_add_u32_e32 v33, 0x6200, v4
	v_lshl_add_u64 v[4:5], v[2:3], 0, s[0:1]
	s_mov_b64 s[0:1], 0x12000
	v_lshl_add_u64 v[10:11], s[64:65], 0, v[0:1]
	v_mul_u32_u24_e32 v0, 0x50, v13
	v_lshl_add_u64 v[6:7], v[2:3], 0, s[0:1]
	s_mov_b64 s[0:1], 0x1b000
	v_readlane_b32 s25, v252, 0
	v_add3_u32 v0, v0, v12, 0
	v_add_u32_e32 v31, 0xfffffe00, v204
	v_add_u32_e32 v34, 0xc0, v28
	v_add_u32_e32 v35, 0x180, v28
	v_lshl_add_u64 v[8:9], v[2:3], 0, s[0:1]
	v_add_u32_e32 v36, 0x240, v28
	s_lshl_b32 s18, s25, 5
	s_lshl_b32 s19, s68, 5
	v_add_u32_e32 v37, 0xf200, v0
	s_movk_i32 s20, 0xffd0
	s_movk_i32 s21, 0x3ff
	v_mov_b32_e32 v38, 0x24000
	s_mov_b64 s[4:5], 0x2000
	s_movk_i32 s24, 0x6ff
	s_mov_b64 s[6:7], 0x40000
	s_branch .LBB0_233
